# HGRN2 chain interval 2: P tiles and next-chunk cumulative-decay tiles software-pipelined (all LDS reads up front, distinct registers, counted lgkmcnt)
# baseline (speedup 1.0000x reference)
.LBB0_480:
	ds_read_b64_tr_b16 v[40:41], v104 offset:27648
	ds_read_b64_tr_b16 v[42:43], v104 offset:28224
	v_exp_f32_e32 v60, v118
	ds_read_b128 v[44:47], v109 offset:36864
	v_exp_f32_e32 v61, v119
	v_exp_f32_e32 v62, v120
	v_exp_f32_e32 v63, v121
	ds_read_b128 v[36:39], v108 offset:36864
	s_waitcnt lgkmcnt(1)
	v_mfma_f32_16x16x32_bf16 v[44:47], v[40:43], v[44:47], 0
	ds_read_b64_tr_b16 v[48:49], v104 offset:18432
	ds_read_b64_tr_b16 v[50:51], v104 offset:19008
	ds_read_b64_tr_b16 v[52:53], v104 offset:32256
	v_pk_mul_f32 v[34:35], v[34:35], v[62:63]
	v_pk_mul_f32 v[32:33], v[32:33], v[60:61]
	s_waitcnt lgkmcnt(3)
	v_mfma_f32_16x16x32_bf16 v[36:39], v[40:43], v[36:39], 0
	ds_read_b64_tr_b16 v[40:41], v106 offset:27648
	ds_read_b64_tr_b16 v[42:43], v106 offset:28224
	ds_read_b64_tr_b16 v[56:57], v107 offset:27648
	ds_read_b64_tr_b16 v[58:59], v107 offset:28224
	ds_read_b64_tr_b16 v[54:55], v104 offset:32832
	v_pk_mul_f32 v[30:31], v[30:31], v[62:63]
	v_pk_mul_f32 v[28:29], v[28:29], v[60:61]
	s_waitcnt lgkmcnt(3)
	v_mfma_f32_16x16x32_bf16 v[32:35], v[48:51], v[40:43], v[32:35]
	s_add_i32 s47, s47, 2
	s_and_b64 vcc, exec, s[60:61]
	s_mov_b32 s60, 0xffff0000
	s_waitcnt lgkmcnt(1)
	v_mfma_f32_16x16x32_bf16 v[40:43], v[48:51], v[56:59], v[28:31]
	s_nop 2
	ds_read_b128 v[28:31], v109 offset:36928
	ds_read_b64_tr_b16 v[48:49], v104 offset:23616
	ds_read_b128 v[56:59], v108 offset:36928
	s_movk_i32 s61, 0x90
	s_waitcnt lgkmcnt(2)
	v_mfma_f32_16x16x32_bf16 v[60:63], v[52:55], v[28:31], v[44:47]
	s_nop 2
	ds_read_b64_tr_b16 v[46:47], v104 offset:23040
	ds_read_b64_tr_b16 v[28:29], v106 offset:32256
	s_waitcnt lgkmcnt(2)
	v_mfma_f32_16x16x32_bf16 v[36:39], v[52:55], v[56:59], v[36:39]
	ds_read_b64_tr_b16 v[30:31], v106 offset:32832
	ds_read_b64_tr_b16 v[50:51], v107 offset:32256
	ds_read_b64_tr_b16 v[52:53], v107 offset:32832
	ds_read_b128 v[54:57], v105 offset:55296
	s_waitcnt lgkmcnt(3)
	v_mfma_f32_16x16x32_bf16 v[28:31], v[46:49], v[28:31], v[32:35]
	s_waitcnt lgkmcnt(1)
	v_mfma_f32_16x16x32_bf16 v[32:35], v[46:49], v[50:53], v[40:43]
	s_nop 2
	ds_read_b128 v[40:43], v109 offset:9216
	ds_read_b128 v[44:47], v108 offset:9216
	ds_read_b128 v[48:51], v105 offset:55360
	v_cvt_pk_bf16_f32 v52, v28, v29
	s_waitcnt lgkmcnt(1)
	v_mfma_f32_16x16x32_bf16 v[36:39], v[54:57], v[44:47], v[36:39]
	ds_read_b128 v[44:47], v109 offset:9280
	v_cvt_pk_bf16_f32 v53, v30, v31
	v_mfma_f32_16x16x32_bf16 v[40:43], v[54:57], v[40:43], v[60:63]
	s_waitcnt lgkmcnt(0)
	v_mfma_f32_16x16x32_bf16 v[40:43], v[48:51], v[44:47], v[40:43]
	ds_read_b128 v[44:47], v108 offset:9280
	ds_write_b64 v113, v[52:53] offset:46080
	s_waitcnt lgkmcnt(1)
	v_mfma_f32_16x16x32_bf16 v[36:39], v[48:51], v[44:47], v[36:39]
	v_cvt_pk_bf16_f32 v44, v32, v33
	v_cvt_pk_bf16_f32 v45, v34, v35
	ds_write_b64 v112, v[44:45] offset:46080
	v_add_u32_e32 v44, s34, v75
	v_lshl_or_b32 v180, v44, 10, v76
	v_cvt_pk_bf16_f32 v40, v40, v41
	v_cvt_pk_bf16_f32 v41, v42, v43
	v_lshl_add_u64 v[42:43], v[180:181], 1, s[92:93]
	global_store_dwordx2 v[42:43], v[40:41], off
	v_add_u32_e32 v40, s34, v77
	v_lshl_or_b32 v180, v40, 10, v76
	v_cvt_pk_bf16_f32 v36, v36, v37
	v_cvt_pk_bf16_f32 v37, v38, v39
	v_lshl_add_u64 v[38:39], v[180:181], 1, s[92:93]
	global_store_dwordx2 v[38:39], v[36:37], off
	s_waitcnt lgkmcnt(0)
	s_barrier
	s_cbranch_vccnz .LBB0_541

.LBB0_490:
	v_add_u32_e32 v111, v78, v64
	v_add_u32_e32 v110, v79, v64
	ds_read_b128 v[36:39], v98 offset:64512
	ds_read_b128 v[44:47], v111
	ds_read_b128 v[40:43], v98 offset:64576
	ds_read_b128 v[48:51], v111 offset:64
	v_add_u32_e32 v118, s0, v64
	ds_read_b128 v[118:121], v118
	v_cndmask_b32_e64 v170, 0, 1, s[90:91]
	v_cmp_ne_u32_e64 s[38:39], 1, v170
	v_cndmask_b32_e64 v170, 0, 1, s[50:51]
	v_cmp_ne_u32_e64 s[36:37], 1, v170
	s_andn2_b64 vcc, exec, s[88:89]
	s_cbranch_vccnz .Lh2a_w01
	ds_read_b64_tr_b16 v[122:123], v102
	ds_read_b64_tr_b16 v[124:125], v102 offset:576
	ds_read_b128 v[126:129], v103
	ds_read_b64_tr_b16 v[130:131], v102 offset:4608
	ds_read_b64_tr_b16 v[132:133], v102 offset:5184
	ds_read_b128 v[134:137], v103 offset:64
	v_add_u32_e32 v170, v67, v65
	v_add_u32_e32 v171, v69, v64
	s_waitcnt lgkmcnt(9)
	v_mfma_f32_16x16x32_bf16 v[36:39], v[36:39], v[44:47], 0
	s_waitcnt lgkmcnt(7)
	v_mfma_f32_16x16x32_bf16 v[36:39], v[40:43], v[48:51], v[36:39]
	ds_read_b64_tr_b16 v[138:139], v170
	ds_read_b64_tr_b16 v[140:141], v170 offset:576
	ds_read_b128 v[142:145], v171
	ds_read_b64_tr_b16 v[146:147], v170 offset:4608
	ds_read_b64_tr_b16 v[148:149], v170 offset:5184
	ds_read_b128 v[150:153], v171 offset:64
	s_waitcnt lgkmcnt(9)
	v_mfma_f32_16x16x32_bf16 v[122:125], v[122:125], v[126:129], 0
	s_waitcnt lgkmcnt(6)
	v_mfma_f32_16x16x32_bf16 v[122:125], v[130:133], v[134:137], v[122:125]
	v_cndmask_b32_e64 v36, 0, v36, s[14:15]
	v_cndmask_b32_e64 v37, 0, v37, s[16:17]
	v_cndmask_b32_e64 v38, 0, v38, s[18:19]
	v_cndmask_b32_e64 v39, 0, v39, s[20:21]
	v_cvt_pk_bf16_f32 v36, v36, v37
	v_cvt_pk_bf16_f32 v37, v38, v39
	ds_write_b64 v99, v[36:37] offset:36864
	s_andn2_b64 vcc, exec, s[56:57]
	s_cbranch_vccnz .Lh2a_w67
	v_add_u32_e32 v172, v70, v65
	v_add_u32_e32 v173, v71, v64
	ds_read_b64_tr_b16 v[154:155], v172
	ds_read_b64_tr_b16 v[156:157], v172 offset:576
	ds_read_b128 v[158:161], v173
	ds_read_b64_tr_b16 v[162:163], v172 offset:4608
	ds_read_b64_tr_b16 v[164:165], v172 offset:5184
	ds_read_b128 v[166:169], v173 offset:64
	s_waitcnt lgkmcnt(10)
	v_mfma_f32_16x16x32_bf16 v[138:141], v[138:141], v[142:145], 0
	s_waitcnt lgkmcnt(7)
	v_mfma_f32_16x16x32_bf16 v[138:141], v[146:149], v[150:153], v[138:141]
	ds_write_b128 v89, v[122:125]
	s_waitcnt lgkmcnt(4)
	v_mfma_f32_16x16x32_bf16 v[154:157], v[154:157], v[158:161], 0
	s_waitcnt lgkmcnt(1)
	v_mfma_f32_16x16x32_bf16 v[154:157], v[162:165], v[166:169], v[154:157]
	s_nop 2
	ds_write_b128 v90, v[138:141]
	s_nop 6
	ds_write_b128 v91, v[154:157]
	s_branch .LBB0_496
.Lh2a_w67:
	s_waitcnt lgkmcnt(4)
	v_mfma_f32_16x16x32_bf16 v[138:141], v[138:141], v[142:145], 0
	s_waitcnt lgkmcnt(1)
	v_mfma_f32_16x16x32_bf16 v[138:141], v[146:149], v[150:153], v[138:141]
	ds_write_b128 v89, v[122:125]
	s_nop 6
	ds_write_b128 v90, v[138:141]
	s_branch .LBB0_496
.Lh2a_w01:
	ds_read_b128 v[122:125], v100 offset:64512
	ds_read_b128 v[126:129], v110
	ds_read_b128 v[130:133], v100 offset:64576
	ds_read_b128 v[134:137], v110 offset:64
	s_waitcnt lgkmcnt(7)
	v_mfma_f32_16x16x32_bf16 v[36:39], v[36:39], v[44:47], 0
	s_waitcnt lgkmcnt(5)
	v_mfma_f32_16x16x32_bf16 v[36:39], v[40:43], v[48:51], v[36:39]
	s_waitcnt lgkmcnt(2)
	v_mfma_f32_16x16x32_bf16 v[122:125], v[122:125], v[126:129], 0
	s_waitcnt lgkmcnt(0)
	v_mfma_f32_16x16x32_bf16 v[122:125], v[130:133], v[134:137], v[122:125]
	s_nop 3
	v_cndmask_b32_e64 v36, 0, v36, s[14:15]
	v_cndmask_b32_e64 v37, 0, v37, s[16:17]
	v_cndmask_b32_e64 v38, 0, v38, s[18:19]
	v_cndmask_b32_e64 v39, 0, v39, s[20:21]
	v_cvt_pk_bf16_f32 v36, v36, v37
	v_cvt_pk_bf16_f32 v37, v38, v39
	ds_write_b64 v99, v[36:37] offset:36864
	v_cndmask_b32_e64 v122, 0, v122, s[22:23]
	v_cndmask_b32_e64 v123, 0, v123, s[24:25]
	v_cndmask_b32_e64 v124, 0, v124, s[26:27]
	v_cndmask_b32_e64 v125, 0, v125, s[28:29]
	v_cvt_pk_bf16_f32 v122, v122, v123
	v_cvt_pk_bf16_f32 v123, v124, v125
	ds_write_b64 v101, v[122:123] offset:36864

.LBB0_508:
	v_add_u32_e32 v109, v72, v64
	v_add_u32_e32 v108, v73, v64
	ds_read_b64_tr_b16 v[40:41], v104 offset:27648
	ds_read_b64_tr_b16 v[42:43], v104 offset:28224
	v_exp_f32_e32 v60, v118
	v_exp_f32_e32 v61, v119
	ds_read_b128 v[44:47], v109 offset:36864
	v_exp_f32_e32 v62, v120
	v_exp_f32_e32 v63, v121
	ds_read_b128 v[36:39], v108 offset:36864
	s_waitcnt lgkmcnt(1)
	v_mfma_f32_16x16x32_bf16 v[44:47], v[40:43], v[44:47], 0
	ds_read_b64_tr_b16 v[48:49], v104 offset:18432
	ds_read_b64_tr_b16 v[50:51], v104 offset:19008
	ds_read_b64_tr_b16 v[52:53], v104 offset:32256
	v_pk_mul_f32 v[30:31], v[30:31], v[62:63]
	v_pk_mul_f32 v[28:29], v[28:29], v[60:61]
	s_waitcnt lgkmcnt(3)
	v_mfma_f32_16x16x32_bf16 v[36:39], v[40:43], v[36:39], 0
	ds_read_b64_tr_b16 v[40:41], v106 offset:27648
	ds_read_b64_tr_b16 v[42:43], v106 offset:28224
	ds_read_b64_tr_b16 v[56:57], v107 offset:27648
	ds_read_b64_tr_b16 v[58:59], v107 offset:28224
	ds_read_b64_tr_b16 v[54:55], v104 offset:32832
	v_pk_mul_f32 v[34:35], v[34:35], v[62:63]
	v_pk_mul_f32 v[32:33], v[32:33], v[60:61]
	s_waitcnt lgkmcnt(3)
	v_mfma_f32_16x16x32_bf16 v[28:31], v[48:51], v[40:43], v[28:31]
	v_add_u32_e32 v113, v72, v74
	v_add_u32_e32 v112, v73, v74
	v_readlane_b32 s4, v255, 10
	s_waitcnt lgkmcnt(1)
	v_mfma_f32_16x16x32_bf16 v[40:43], v[48:51], v[56:59], v[32:35]
	s_nop 2
	ds_read_b128 v[32:35], v109 offset:36928
	ds_read_b64_tr_b16 v[48:49], v104 offset:23616
	ds_read_b128 v[56:59], v108 offset:36928
	s_and_b64 vcc, exec, s[34:35]
	s_waitcnt lgkmcnt(2)
	v_mfma_f32_16x16x32_bf16 v[60:63], v[52:55], v[32:35], v[44:47]
	s_nop 2
	ds_read_b64_tr_b16 v[46:47], v104 offset:23040
	ds_read_b64_tr_b16 v[32:33], v106 offset:32256
	s_waitcnt lgkmcnt(2)
	v_mfma_f32_16x16x32_bf16 v[36:39], v[52:55], v[56:59], v[36:39]
	ds_read_b64_tr_b16 v[34:35], v106 offset:32832
	ds_read_b64_tr_b16 v[50:51], v107 offset:32256
	ds_read_b64_tr_b16 v[52:53], v107 offset:32832
	ds_read_b128 v[54:57], v105 offset:46080
	s_waitcnt lgkmcnt(3)
	v_mfma_f32_16x16x32_bf16 v[32:35], v[46:49], v[32:35], v[28:31]
	s_waitcnt lgkmcnt(1)
	v_mfma_f32_16x16x32_bf16 v[28:31], v[46:49], v[50:53], v[40:43]
	s_nop 2
	ds_read_b128 v[40:43], v109 offset:9216
	ds_read_b128 v[44:47], v108 offset:9216
	ds_read_b128 v[48:51], v105 offset:46144
	s_waitcnt lgkmcnt(1)
	v_mfma_f32_16x16x32_bf16 v[36:39], v[54:57], v[44:47], v[36:39]
	ds_read_b128 v[44:47], v109 offset:9280
	v_mfma_f32_16x16x32_bf16 v[40:43], v[54:57], v[40:43], v[60:63]
	s_waitcnt lgkmcnt(0)
	v_mfma_f32_16x16x32_bf16 v[40:43], v[48:51], v[44:47], v[40:43]
	ds_read_b128 v[44:47], v108 offset:9280
	s_waitcnt lgkmcnt(0)
	v_mfma_f32_16x16x32_bf16 v[36:39], v[48:51], v[44:47], v[36:39]
	v_cvt_pk_bf16_f32 v44, v32, v33
	v_cvt_pk_bf16_f32 v45, v34, v35
	ds_write_b64 v113, v[44:45] offset:55296
	v_cvt_pk_bf16_f32 v44, v28, v29
	v_cvt_pk_bf16_f32 v45, v30, v31
	ds_write_b64 v112, v[44:45] offset:55296
	v_add_u32_e32 v44, s48, v75
	v_lshl_or_b32 v180, v44, 10, v76
	v_cvt_pk_bf16_f32 v40, v40, v41
	v_cvt_pk_bf16_f32 v41, v42, v43
	v_lshl_add_u64 v[42:43], v[180:181], 1, s[92:93]
	global_store_dwordx2 v[42:43], v[40:41], off
	v_add_u32_e32 v40, s48, v77
	v_lshl_or_b32 v180, v40, 10, v76
	v_cvt_pk_bf16_f32 v36, v36, v37
	v_cvt_pk_bf16_f32 v37, v38, v39
	v_lshl_add_u64 v[38:39], v[180:181], 1, s[92:93]
	global_store_dwordx2 v[38:39], v[36:37], off
	v_mov_b32_e32 v36, v68
	s_waitcnt lgkmcnt(0)
	s_barrier
	v_mov_b32_e32 v43, 0
	v_lshrrev_b32_e32 v37, 3, v36
	v_and_or_b32 v40, v37, 7, s70
	v_and_b32_e32 v41, 7, v36
	v_lshlrev_b32_e32 v36, 8, v40
	v_lshlrev_b32_e32 v37, 5, v41
	v_add3_u32 v36, s4, v36, v37
	ds_read_b128 v[44:47], v36
	ds_read_b128 v[36:39], v36 offset:16
	v_mul_lo_u32 v116, v40, s72
	v_lshlrev_b32_e32 v117, 4, v41
	v_lshlrev_b32_e32 v115, 3, v41
	v_add3_u32 v114, 0, v116, v117
	v_mov_b32_e32 v42, 0
	v_mov_b32_e32 v41, 0
	v_mov_b32_e32 v40, 0
	v_mov_b32_e32 v51, 0
	v_mov_b32_e32 v50, 0
	v_mov_b32_e32 v49, 0
	v_mov_b32_e32 v48, 0
	ds_write_b128 v114, v[24:27] offset:27648
	s_cbranch_vccnz .LBB0_510
	v_lshl_add_u32 v40, v115, 2, s62
	ds_read_b128 v[48:51], v40
	ds_read_b128 v[40:43], v40 offset:16

.LBB0_519:
	s_mov_b32 s54, 0xe10000
	s_movk_i32 s55, 0x1fff
	s_movk_i32 s63, 0xe00
	v_readlane_b32 s72, v255, 5
	ds_read_b128 v[36:39], v98 offset:64512
	ds_read_b128 v[44:47], v111
	ds_read_b128 v[40:43], v98 offset:64576
	ds_read_b128 v[48:51], v111 offset:64
	v_add_u32_e32 v118, s33, v64
	ds_read_b128 v[118:121], v118
	s_andn2_b64 vcc, exec, s[88:89]
	s_cbranch_vccnz .Lh2b_w01
	s_andn2_b64 vcc, exec, s[34:35]
	s_cbranch_vccnz .Lh2b_ponly
	ds_read_b64_tr_b16 v[122:123], v102
	ds_read_b64_tr_b16 v[124:125], v102 offset:576
	ds_read_b128 v[126:129], v103
	ds_read_b64_tr_b16 v[130:131], v92 offset:4608
	ds_read_b64_tr_b16 v[132:133], v92 offset:5184
	ds_read_b128 v[134:137], v103 offset:64
	v_add_u32_e32 v170, v67, v65
	v_add_u32_e32 v171, v69, v64
	s_waitcnt lgkmcnt(9)
	v_mfma_f32_16x16x32_bf16 v[36:39], v[36:39], v[44:47], 0
	s_waitcnt lgkmcnt(7)
	v_mfma_f32_16x16x32_bf16 v[36:39], v[40:43], v[48:51], v[36:39]
	ds_read_b64_tr_b16 v[138:139], v170
	ds_read_b64_tr_b16 v[140:141], v170 offset:576
	ds_read_b128 v[142:145], v171
	ds_read_b64_tr_b16 v[146:147], v94 offset:4608
	ds_read_b64_tr_b16 v[148:149], v94 offset:5184
	ds_read_b128 v[150:153], v171 offset:64
	s_waitcnt lgkmcnt(9)
	v_mfma_f32_16x16x32_bf16 v[122:125], v[122:125], v[126:129], 0
	s_waitcnt lgkmcnt(6)
	v_mfma_f32_16x16x32_bf16 v[122:125], v[130:133], v[134:137], v[122:125]
	v_cndmask_b32_e64 v36, 0, v36, s[14:15]
	v_cndmask_b32_e64 v37, 0, v37, s[16:17]
	v_cndmask_b32_e64 v38, 0, v38, s[18:19]
	v_cndmask_b32_e64 v39, 0, v39, s[20:21]
	v_cvt_pk_bf16_f32 v36, v36, v37
	v_cvt_pk_bf16_f32 v37, v38, v39
	ds_write_b64 v99, v[36:37] offset:36864
	s_andn2_b64 vcc, exec, s[56:57]
	s_cbranch_vccnz .Lh2b_w67
	v_add_u32_e32 v172, v70, v65
	v_add_u32_e32 v173, v71, v64
	ds_read_b64_tr_b16 v[154:155], v172
	ds_read_b64_tr_b16 v[156:157], v172 offset:576
	ds_read_b128 v[158:161], v173
	ds_read_b64_tr_b16 v[162:163], v96 offset:4608
	ds_read_b64_tr_b16 v[164:165], v96 offset:5184
	ds_read_b128 v[166:169], v173 offset:64
	s_waitcnt lgkmcnt(10)
	v_mfma_f32_16x16x32_bf16 v[138:141], v[138:141], v[142:145], 0
	s_waitcnt lgkmcnt(7)
	v_mfma_f32_16x16x32_bf16 v[138:141], v[146:149], v[150:153], v[138:141]
	ds_write_b128 v93, v[122:125]
	s_waitcnt lgkmcnt(4)
	v_mfma_f32_16x16x32_bf16 v[154:157], v[154:157], v[158:161], 0
	s_waitcnt lgkmcnt(1)
	v_mfma_f32_16x16x32_bf16 v[154:157], v[162:165], v[166:169], v[154:157]
	s_nop 2
	ds_write_b128 v95, v[138:141]
	s_nop 6
	ds_write_b128 v97, v[154:157]
	s_branch .LBB0_525
.Lh2b_w67:
	s_waitcnt lgkmcnt(4)
	v_mfma_f32_16x16x32_bf16 v[138:141], v[138:141], v[142:145], 0
	s_waitcnt lgkmcnt(1)
	v_mfma_f32_16x16x32_bf16 v[138:141], v[146:149], v[150:153], v[138:141]
	ds_write_b128 v93, v[122:125]
	s_nop 6
	ds_write_b128 v95, v[138:141]
	s_branch .LBB0_525
.Lh2b_ponly:
	s_waitcnt lgkmcnt(3)
	v_mfma_f32_16x16x32_bf16 v[36:39], v[36:39], v[44:47], 0
	s_waitcnt lgkmcnt(1)
	v_mfma_f32_16x16x32_bf16 v[36:39], v[40:43], v[48:51], v[36:39]
	s_nop 7
	v_cndmask_b32_e64 v36, 0, v36, s[14:15]
	v_cndmask_b32_e64 v37, 0, v37, s[16:17]
	v_cndmask_b32_e64 v38, 0, v38, s[18:19]
	v_cndmask_b32_e64 v39, 0, v39, s[20:21]
	v_cvt_pk_bf16_f32 v36, v36, v37
	v_cvt_pk_bf16_f32 v37, v38, v39
	ds_write_b64 v99, v[36:37] offset:36864
	s_branch .LBB0_525
